# P0 GEMV item head: both silu(c) staging loads issued together; weight-row prefetch started before the staging wait
# baseline (speedup 1.0000x reference)
; __device__ __forceinline__ float silu_f(float x) { return x * __builtin_amdgcn_rcpf(1.f + __expf(-x)); }
; __device__ __forceinline__ void p0_prologue(const Args& A, char* lds, int vcu, int G) {
;     ...
;     for (int item = blockIdx.x; item < 2 * KS * 6; item += G) {
;         const int l = item / (KS * 6), r = item % (KS * 6), kc = r / 6, cb = r % 6;
;         __syncthreads();
;         for (int i = tid; i < 1024; i += NTHR) { const int b = i >> 7, k = i & 127; const float cv = A.in[I_C][b * 1024 + kc * 128 + k]; sc[i] = silu_f(cv); }
;         __syncthreads();
;         const int col = cb * 512 + tid; float acc[8];
; #pragma unroll
;         for (int b = 0; b < 8; ++b) acc[b] = 0.f;
;         const float* wp = A.in[I_ADAW] + ((size_t)l * 1024 + kc * 128) * 3072 + col;
; #pragma unroll 16
;         for (int k = 0; k < 128; ++k) { const float w = __builtin_nontemporal_load(&wp[(size_t)k * 3072]);
; #pragma unroll
;             for (int b = 0; b < 8; ++b) acc[b] += sc[b * 128 + k] * w; }
; #pragma unroll
;         for (int b = 0; b < 8; ++b) modp[((size_t)(kc * 2 + l) * 8 + b) * 3072 + col] = acc[b];
.LBB0_289:
	s_mul_hi_i32 s20, s53, 0x2aaaaaab
	s_lshr_b32 s21, s20, 31
	s_ashr_i32 s20, s20, 3
	s_add_i32 s20, s20, s21
	s_mul_i32 s21, s20, 48
	s_sub_i32 s21, s53, s21
	s_mul_i32 s22, s21, 43
	s_bfe_u32 s23, s22, 0x1000f
	s_bfe_u32 s56, s22, 0x80008
	s_add_i32 s56, s56, s23
	s_sext_i32_i8 s54, s56
	s_lshl_b32 s55, s54, 7
	v_or_b32_e32 v0, s55, v14
	v_and_b32_e32 v4, 0xfffffc00, v17
	v_add_u32_e32 v4, v4, v0
	v_ashrrev_i32_e32 v5, 31, v4
	v_lshl_add_u64 v[4:5], v[4:5], 2, s[16:17]
	v_add_u32_e32 v6, 0x1000, v17
	v_and_b32_e32 v6, 0xfffffc00, v6
	v_add_u32_e32 v6, v6, v0
	v_ashrrev_i32_e32 v7, 31, v6
	v_lshl_add_u64 v[6:7], v[6:7], 2, s[16:17]
	global_load_dword v4, v[4:5], off
	global_load_dword v6, v[6:7], off
	s_mul_i32 s100, s56, 6
	s_sub_i32 s100, s21, s100
	s_lshl_b32 s100, s100, 11
	s_lshl_b32 s98, s20, 10
	s_add_i32 s98, s98, s55
	s_mul_hi_u32 s99, s98, 0x3000
	s_mul_i32 s98, s98, 0x3000
	s_add_u32 s98, s33, s98
	s_addc_u32 s99, s3, s99
	s_add_u32 s98, s98, s100
	s_addc_u32 s99, s99, 0
	v_readfirstlane_b32 s100, v220
	s_nop 0
	s_lshr_b32 s100, s100, 6
	s_lshl_b32 s100, s100, 8
	s_add_u32 s98, s98, s100
	s_addc_u32 s99, s99, 0
	v_and_b32_e32 v255, 63, v220
	v_lshlrev_b32_e32 v255, 2, v255
	global_load_dword v180, v255, s[98:99] nt
	s_add_u32 s100, s98, 0x3000
	s_addc_u32 s101, s99, 0
	global_load_dword v181, v255, s[100:101] nt
	s_add_u32 s100, s98, 0x6000
	s_addc_u32 s101, s99, 0
	global_load_dword v182, v255, s[100:101] nt
	s_add_u32 s100, s98, 0x9000
	s_addc_u32 s101, s99, 0
	global_load_dword v183, v255, s[100:101] nt
	s_add_u32 s100, s98, 0xc000
	s_addc_u32 s101, s99, 0
	global_load_dword v184, v255, s[100:101] nt
	s_add_u32 s100, s98, 0xf000
	s_addc_u32 s101, s99, 0
	global_load_dword v185, v255, s[100:101] nt
	s_add_u32 s100, s98, 0x12000
	s_addc_u32 s101, s99, 0
	global_load_dword v186, v255, s[100:101] nt
	s_add_u32 s100, s98, 0x15000
	s_addc_u32 s101, s99, 0
	global_load_dword v187, v255, s[100:101] nt
	s_add_u32 s100, s98, 0x18000
	s_addc_u32 s101, s99, 0
	global_load_dword v188, v255, s[100:101] nt
	s_add_u32 s100, s98, 0x1b000
	s_addc_u32 s101, s99, 0
	global_load_dword v189, v255, s[100:101] nt
	s_add_u32 s100, s98, 0x1e000
	s_addc_u32 s101, s99, 0
	global_load_dword v190, v255, s[100:101] nt
	s_add_u32 s100, s98, 0x21000
	s_addc_u32 s101, s99, 0
	global_load_dword v191, v255, s[100:101] nt
	s_add_u32 s100, s98, 0x24000
	s_addc_u32 s101, s99, 0
	global_load_dword v192, v255, s[100:101] nt
	s_add_u32 s100, s98, 0x27000
	s_addc_u32 s101, s99, 0
	global_load_dword v193, v255, s[100:101] nt
	s_add_u32 s100, s98, 0x2a000
	s_addc_u32 s101, s99, 0
	global_load_dword v194, v255, s[100:101] nt
	s_add_u32 s100, s98, 0x2d000
	s_addc_u32 s101, s99, 0
	global_load_dword v195, v255, s[100:101] nt
	s_add_u32 s100, s98, 0x30000
	s_addc_u32 s101, s99, 0
	global_load_dword v196, v255, s[100:101] nt
	s_add_u32 s100, s98, 0x33000
	s_addc_u32 s101, s99, 0
	global_load_dword v197, v255, s[100:101] nt
	s_add_u32 s100, s98, 0x36000
	s_addc_u32 s101, s99, 0
	global_load_dword v198, v255, s[100:101] nt
	s_add_u32 s100, s98, 0x39000
	s_addc_u32 s101, s99, 0
	global_load_dword v199, v255, s[100:101] nt
	s_add_u32 s100, s98, 0x3c000
	s_addc_u32 s101, s99, 0
	global_load_dword v200, v255, s[100:101] nt
	s_add_u32 s100, s98, 0x3f000
	s_addc_u32 s101, s99, 0
	global_load_dword v201, v255, s[100:101] nt
	s_add_u32 s100, s98, 0x42000
	s_addc_u32 s101, s99, 0
	global_load_dword v202, v255, s[100:101] nt
	s_add_u32 s100, s98, 0x45000
	s_addc_u32 s101, s99, 0
	global_load_dword v203, v255, s[100:101] nt
	s_add_u32 s100, s98, 0x48000
	s_addc_u32 s101, s99, 0
	global_load_dword v204, v255, s[100:101] nt
	s_add_u32 s100, s98, 0x4b000
	s_addc_u32 s101, s99, 0
	global_load_dword v205, v255, s[100:101] nt
	s_add_u32 s100, s98, 0x4e000
	s_addc_u32 s101, s99, 0
	global_load_dword v206, v255, s[100:101] nt
	s_add_u32 s100, s98, 0x51000
	s_addc_u32 s101, s99, 0
	global_load_dword v207, v255, s[100:101] nt
	s_add_u32 s100, s98, 0x54000
	s_addc_u32 s101, s99, 0
	global_load_dword v208, v255, s[100:101] nt
	s_add_u32 s100, s98, 0x57000
	s_addc_u32 s101, s99, 0
	global_load_dword v209, v255, s[100:101] nt
	s_add_u32 s100, s98, 0x5a000
	s_addc_u32 s101, s99, 0
	global_load_dword v210, v255, s[100:101] nt
	s_add_u32 s100, s98, 0x5d000
	s_addc_u32 s101, s99, 0
	global_load_dword v211, v255, s[100:101] nt
	s_add_u32 s100, s98, 0x60000
	s_addc_u32 s101, s99, 0
	global_load_dword v212, v255, s[100:101] nt
	s_add_u32 s100, s98, 0x63000
	s_addc_u32 s101, s99, 0
	global_load_dword v213, v255, s[100:101] nt
	s_add_u32 s100, s98, 0x66000
	s_addc_u32 s101, s99, 0
	global_load_dword v214, v255, s[100:101] nt
	s_add_u32 s100, s98, 0x69000
	s_addc_u32 s101, s99, 0
	global_load_dword v215, v255, s[100:101] nt
	s_add_u32 s100, s98, 0x6c000
	s_addc_u32 s101, s99, 0
	global_load_dword v216, v255, s[100:101] nt
	s_add_u32 s100, s98, 0x6f000
	s_addc_u32 s101, s99, 0
	global_load_dword v217, v255, s[100:101] nt
	s_add_u32 s100, s98, 0x72000
	s_addc_u32 s101, s99, 0
	global_load_dword v218, v255, s[100:101] nt
	s_add_u32 s100, s98, 0x75000
	s_addc_u32 s101, s99, 0
	global_load_dword v219, v255, s[100:101] nt
	s_add_u32 s100, s98, 0x78000
	s_addc_u32 s101, s99, 0
	global_load_dword v222, v255, s[100:101] nt
	s_add_u32 s100, s98, 0x7b000
	s_addc_u32 s101, s99, 0
	global_load_dword v223, v255, s[100:101] nt
	s_add_u32 s100, s98, 0x7e000
	s_addc_u32 s101, s99, 0
	global_load_dword v224, v255, s[100:101] nt
	s_add_u32 s100, s98, 0x81000
	s_addc_u32 s101, s99, 0
	global_load_dword v225, v255, s[100:101] nt
	s_add_u32 s100, s98, 0x84000
	s_addc_u32 s101, s99, 0
	global_load_dword v226, v255, s[100:101] nt
	s_add_u32 s100, s98, 0x87000
	s_addc_u32 s101, s99, 0
	global_load_dword v227, v255, s[100:101] nt
	s_add_u32 s100, s98, 0x8a000
	s_addc_u32 s101, s99, 0
	global_load_dword v228, v255, s[100:101] nt
	s_add_u32 s100, s98, 0x8d000
	s_addc_u32 s101, s99, 0
	global_load_dword v229, v255, s[100:101] nt
	s_barrier
	s_waitcnt vmcnt(48)
	v_mul_f32_e32 v5, 0xbfb8aa3b, v4
	v_mul_f32_e32 v7, 0xbfb8aa3b, v6
	v_exp_f32_e32 v5, v5
	v_exp_f32_e32 v7, v7
	s_nop 0
	v_add_f32_e32 v5, 1.0, v5
	v_add_f32_e32 v7, 1.0, v7
	v_rcp_f32_e32 v5, v5
	v_rcp_f32_e32 v7, v7
	s_nop 0
	v_mul_f32_e32 v4, v4, v5
	v_mul_f32_e32 v6, v6, v7
	ds_write_b32 v18, v4
	ds_write_b32 v18, v6 offset:2048
